# rstd-table loads issued after the first tile loads; accumulator zeroing with 64-bit moves; grid-size guard on the workgroup-local seam
# speedup vs baseline: 1.0018x; 1.0018x over previous
; __device__ __forceinline__ void sgu_phase(KP kp, LAS unsigned char* lds, int l) {
;     ...
;     const bool local_map = (gridDim.x == 256);
;     int pm_ = 0, pn_ = 0;
;     { const int c = blockIdx.x, wgid = (c % 8) * 32 + c / 8; pm_ = (wgid / 32) * 8 + ((wgid % 32) % 8); pn_ = (wgid % 32) / 8; }
;     const int n_units = local_map ? 4 : (1024 - (int)blockIdx.x + (int)gridDim.x - 1) / (int)gridDim.x;
;     for (int ui = 0; ui < n_units; ++ui) {
;         const int u = local_map ? ((2 * pm_ + (ui >> 1)) * 8 + 2 * pn_ + (ui & 1)) : ((int)blockIdx.x + ui * (int)gridDim.x);
; __global__ void __launch_bounds__(512) fwd_kernel(Params p) {
;     ...
;         if (ph + 1 < p.ph_hi && k != 3) { xcd_barrier(xbar); if (p.ph_lo < 0) grid.sync(); }
.Lmy_wgsync:
	v_readlane_b32 s0, v251, 44
	v_readlane_b32 s1, v251, 45
	s_nop 0
	s_and_b64 vcc, exec, s[0:1]
	s_cbranch_vccz .Lmy_fullbar
	s_waitcnt vmcnt(0)
	s_barrier
	s_branch .LBB0_9

; #define PG8_BAR __builtin_amdgcn_s_barrier()
; #define PG8_STA(bufoff, gbase, ld) PG8_STAGE(bufoff, gbase, RA0 * (unsigned)(ld) + CC0, RA1 * (unsigned)(ld) + CC1)
; #define PG8_STB(bufoff, gbase, ld) PG8_STAGE(bufoff, gbase, RB0 * (unsigned)(ld) + CC0, RB1 * (unsigned)(ld) + CC1)
; __device__ __forceinline__ void epi_rstd(const float* ssq, int row0, int fq, float (&rs)[2][4]) {
;     ...
;             for (int j = 0; j < 4; ++j) part[ai][m][j] = ssq[(size_t)(4 * fq + j) * M + row0 + ai * 128 + m * 16];
; __device__ __forceinline__ void gemm_phase(LAS unsigned char* lds, const Sched& S, const Epi& E) {
;     ...
;     int R0, C0, R1, C1; stage_rc(tid * 16, R0, C0); stage_rc(tid * 16 + 8192, R1, C1);
;     const int Rb0 = (R0 & ~31) + perm32(R0 & 31), Rb1 = (R1 & ~31) + perm32(R1 & 31);
;     const size_t kstep = (size_t)(BK * 2);
;     const unsigned ldsw = (unsigned)wid * 1024u;
;     const int aoff = lds_byte(wr * 64 + fr, fq * 8), boff = lds_byte(wc * 32 + fr, fq * 8);
;     ...
;     Unit cur, nxt; int ui = 0;
;     if (!S.next(0, cur)) return;
;     f32x4 acc[2][2][4][2];
; #pragma unroll
;     for (int a = 0; a < 2; ++a)
; #pragma unroll
;         for (int b = 0; b < 2; ++b)
; #pragma unroll
;             for (int m = 0; m < 4; ++m)
; #pragma unroll
;                 for (int n = 0; n < 2; ++n) acc[a][b][m][n] = (f32x4){0.f, 0.f, 0.f, 0.f};
;     bf16x8 At[4][2], B0[2][2], B1[2][2];
;     const char* cA = cur.a; const char* cB = cur.b;
;     const unsigned RA0 = R0 * 2, RA1 = R1 * 2, RB0 = Rb0 * 2, RB1 = Rb1 * 2, CC0 = C0 * 2, CC1 = C1 * 2;
;     ...
;     int lda = cur.lda, ldb = cur.ldb;
;     { const size_t hA = (size_t)HALF * lda * 2, hB = (size_t)HALF * ldb * 2;
;     PG8_STB(PG8_SB(0, 0), cB, ldb); PG8_STB(PG8_SB(0, 1), cB + hB, ldb); PG8_STA(PG8_SA(0, 0), cA, lda); PG8_STA(PG8_SA(0, 1), cA + hA, lda);
;     if (wr == 1) PG8_BAR;
.LBB0_253:
	s_andn2_b64 vcc, exec, s[6:7]
	s_cbranch_vccnz .LBB0_355
	v_bfe_i32 v3, v17, 27, 1
	v_lshlrev_b32_e32 v2, 4, v17
	v_lshrrev_b32_e32 v3, 22, v3
	v_add_u32_e32 v3, v2, v3
	v_and_b32_e32 v3, 0xfffffc00, v3
	v_sub_u32_e32 v3, v2, v3
	v_lshrrev_b32_e32 v4, 4, v3
	v_bitop3_b32 v3, v4, v3, 32 bitop3:0x6c
	v_ashrrev_i32_e32 v5, 31, v3
	v_lshrrev_b32_e32 v5, 26, v5
	v_add_u32_e32 v5, v3, v5
	v_ashrrev_i32_e32 v6, 6, v5
	v_and_b32_e32 v5, 0xc0, v5
	v_sub_u32_e32 v3, v3, v5
	v_ashrrev_i16_sdwa v3, v199, sext(v3) dst_sel:DWORD dst_unused:UNUSED_PAD src0_sel:DWORD src1_sel:BYTE_0
	v_add_u32_e32 v2, 0x2000, v2
	v_bfe_i32 v14, v3, 0, 16
	v_ashrrev_i32_e32 v3, 31, v2
	v_lshrrev_b32_e32 v3, 22, v3
	v_add_u32_e32 v3, v2, v3
	v_ashrrev_i32_e32 v15, 10, v3
	v_mul_i32_i24_e32 v3, 0x400, v15
	v_sub_u32_e32 v2, v2, v3
	v_ashrrev_i32_e32 v0, 31, v17
	v_lshrrev_b32_e32 v3, 4, v2
	v_lshrrev_b32_e32 v0, 26, v0
	v_bitop3_b32 v2, v3, v2, 32 bitop3:0x6c
	v_add_u32_e32 v0, v17, v0
	v_ashrrev_i32_e32 v5, 31, v2
	v_ashrrev_i32_e32 v0, 6, v0
	v_lshrrev_b32_e32 v5, 26, v5
	v_lshlrev_b32_e32 v4, 3, v0
	v_add_u32_e32 v5, v2, v5
	v_and_b32_e32 v4, -16, v4
	v_ashrrev_i32_e32 v8, 6, v5
	v_and_b32_e32 v5, 0xc0, v5
	v_add_u32_e32 v4, v6, v4
	v_lshlrev_b32_e32 v3, 3, v15
	v_sub_u32_e32 v2, v2, v5
	v_and_b32_e32 v3, -16, v3
	v_ashrrev_i16_sdwa v2, v199, sext(v2) dst_sel:DWORD dst_unused:UNUSED_PAD src0_sel:DWORD src1_sel:BYTE_0
	v_lshlrev_b32_e32 v235, 1, v4
	v_lshrrev_b32_e32 v5, 2, v4
	v_and_b32_e32 v6, 3, v6
	s_mov_b32 s11, 0x7fffffe0
	v_add_u32_e32 v3, v8, v3
	v_bfe_i32 v16, v2, 0, 16
	v_and_b32_e32 v2, 24, v235
	v_and_b32_e32 v5, 4, v5
	v_and_or_b32 v4, v4, s11, v6
	s_ashr_i32 s7, s2, 6
	v_lshlrev_b32_e32 v7, 5, v0
	v_or3_b32 v2, v4, v5, v2
	v_lshlrev_b32_e32 v236, 1, v3
	v_lshrrev_b32_e32 v5, 2, v3
	v_and_b32_e32 v6, 3, v8
	v_and_b32_e32 v7, 32, v7
	v_lshlrev_b32_e32 v9, 5, v15
	v_and_b32_e32 v4, 24, v236
	v_and_b32_e32 v5, 4, v5
	v_and_or_b32 v3, v3, s11, v6
	s_lshl_b32 s25, s7, 10
	v_and_b32_e32 v9, 32, v9
	v_or3_b32 v3, v3, v5, v4
	v_lshlrev_b32_e32 v237, 1, v2
	v_add_lshl_u32 v194, v7, v14, 1
	v_readlane_b32 s21, v250, 20
	s_add_i32 s34, s25, 0
	v_lshlrev_b32_e32 v238, 1, v3
	v_add_lshl_u32 v196, v9, v16, 1
	v_readlane_b32 s20, v250, 12
	v_mad_u64_u32 v[8:9], s[12:13], v237, s21, v[194:195]
	s_add_i32 m0, s34, 0x10000
	s_ashr_i32 s6, s2, 8
	s_lshl_b32 s11, s20, 8
	s_lshl_b32 s17, s21, 8
	global_load_lds_dwordx4 v8, s[8:9]
	v_mad_u64_u32 v[10:11], s[12:13], v238, s21, v[196:197]
	s_add_i32 m0, s34, 0x12000
	s_add_u32 s12, s8, s17
	global_load_lds_dwordx4 v10, s[8:9]
	s_addc_u32 s13, s9, 0
	s_add_i32 m0, s34, 0x14000
	v_mov_b32_e32 v9, v1
	v_mov_b32_e32 v11, v1
	global_load_lds_dwordx4 v8, s[12:13]
	s_add_i32 m0, s34, 0x16000
	v_lshl_add_u64 v[2:3], s[8:9], 0, v[8:9]
	v_lshl_add_u64 v[6:7], s[12:13], 0, v[8:9]
	v_lshl_add_u64 v[8:9], s[12:13], 0, v[10:11]
	global_load_lds_dwordx4 v10, s[12:13]
	v_mad_u64_u32 v[18:19], s[12:13], v235, s20, v[194:195]
	v_mad_u64_u32 v[20:21], s[12:13], v236, s20, v[196:197]
	s_add_i32 s35, s34, 0x2000
	s_mov_b32 m0, s34
	s_add_u32 s12, s96, s11
	global_load_lds_dwordx4 v18, s[96:97]
	s_mov_b32 m0, s35
	s_addc_u32 s13, s97, 0
	s_add_i32 s39, s34, 0x4000
	global_load_lds_dwordx4 v20, s[96:97]
	s_mov_b32 m0, s39
	s_add_i32 s91, s34, 0x6000
	global_load_lds_dwordx4 v18, s[12:13]
	s_mov_b32 m0, s91
	s_cmp_eq_u32 s6, 1
	global_load_lds_dwordx4 v20, s[12:13]
	v_readlane_b32 s12, v250, 3
	v_readlane_b32 s13, v250, 4
	v_and_b32_e32 v64, 0xff, v195
	v_lshl_add_u32 v64, s95, 8, v64
	v_lshlrev_b32_e32 v64, 2, v64
	s_nop 3
	global_load_dword v66, v64, s[12:13]
	v_add_u32_e32 v65, 0x10000, v64
	global_load_dword v67, v65, s[12:13]
	v_add_u32_e32 v65, 0x20000, v64
	global_load_dword v68, v65, s[12:13]
	v_add_u32_e32 v65, 0x30000, v64
	global_load_dword v69, v65, s[12:13]
	v_add_u32_e32 v65, 0x40000, v64
	global_load_dword v70, v65, s[12:13]
	v_add_u32_e32 v65, 0x50000, v64
	global_load_dword v71, v65, s[12:13]
	v_add_u32_e32 v65, 0x60000, v64
	global_load_dword v72, v65, s[12:13]
	v_add_u32_e32 v65, 0x70000, v64
	global_load_dword v73, v65, s[12:13]
	v_add_u32_e32 v65, 0x80000, v64
	global_load_dword v74, v65, s[12:13]
	v_add_u32_e32 v65, 0x90000, v64
	global_load_dword v75, v65, s[12:13]
	v_add_u32_e32 v65, 0xa0000, v64
	global_load_dword v76, v65, s[12:13]
	v_add_u32_e32 v65, 0xb0000, v64
	global_load_dword v77, v65, s[12:13]
	v_add_u32_e32 v65, 0xc0000, v64
	global_load_dword v78, v65, s[12:13]
	v_add_u32_e32 v65, 0xd0000, v64
	global_load_dword v79, v65, s[12:13]
	v_add_u32_e32 v65, 0xe0000, v64
	global_load_dword v80, v65, s[12:13]
	v_add_u32_e32 v65, 0xf0000, v64
	global_load_dword v81, v65, s[12:13]
	v_mov_b32_e32 v19, v1
	v_mov_b32_e32 v21, v1
	s_cselect_b64 s[12:13], -1, 0
	v_lshl_add_u64 v[4:5], s[8:9], 0, v[10:11]
	v_lshl_add_u64 v[10:11], s[96:97], 0, v[18:19]
	v_lshl_add_u64 v[12:13], s[96:97], 0, v[20:21]
	v_writelane_b32 v250, s12, 25
	s_cmp_lg_u32 s6, 1
	s_nop 0
	v_writelane_b32 v250, s13, 26
	s_cbranch_scc1 .LBB0_256
	s_barrier
; #define PG8_WAIT_V(n) asm volatile("s_waitcnt vmcnt(" #n ")" ::: "memory")
; #define PG8_BAR __builtin_amdgcn_s_barrier()
; #define PG8_STA(bufoff, gbase, ld) PG8_STAGE(bufoff, gbase, RA0 * (unsigned)(ld) + CC0, RA1 * (unsigned)(ld) + CC1)
; #define PG8_STB(bufoff, gbase, ld) PG8_STAGE(bufoff, gbase, RB0 * (unsigned)(ld) + CC0, RB1 * (unsigned)(ld) + CC1)
; __device__ __forceinline__ void epi_rstd(const float* ssq, int row0, int fq, float (&rs)[2][4]) {
;     ...
;         for (int m = 0; m < 4; ++m) { float t = (part[ai][m][0] + part[ai][m][1]) + (part[ai][m][2] + part[ai][m][3]); t += __shfl_xor(t, 16); t += __shfl_xor(t, 32); rs[ai][m] = __builtin_amdgcn_rsqf(t * (1.0f / 1024.0f) + EPS); }
; __device__ __forceinline__ void gemm_phase(LAS unsigned char* lds, const Sched& S, const Epi& E) {
;     ...
;     PG8_WAIT_V(2); PG8_BAR;
;     PG8_STB(PG8_SB(1, 0), cB + kstep, ldb); PG8_STA(PG8_SA(1, 0), cA + kstep, lda); PG8_STB(PG8_SB(1, 1), cB + hB + kstep, ldb);
;     PG8_WAIT_V(6); PG8_BAR; }
;     for (;;) {
;         const bool has_next = S.next(ui + 1, nxt);
;         const char* nA = has_next ? nxt.a : cA; const char* nB = has_next ? nxt.b : cB;
;         const int nlda = has_next ? nxt.lda : lda, nldb = has_next ? nxt.ldb : ldb;
;         const size_t hA = (size_t)HALF * lda * 2;
;         const int nt = cur.nt;
;         const int nt_main = has_next ? nt : nt - 2;
.LBB0_256:
	v_bfe_u32 v19, v17, 4, 2
	v_and_b32_e32 v18, 15, v17
	v_lshlrev_b32_e32 v21, 4, v19
	v_lshlrev_b32_e32 v17, 2, v17
	s_and_b32 s11, s7, 3
	v_lshl_or_b32 v239, s6, 6, v18
	v_lshl_or_b32 v18, v18, 6, v21
	s_lshl_b32 s6, s6, 13
	v_and_b32_e32 v17, 32, v17
	v_bitop3_b32 v240, v18, s6, v17 bitop3:0xde
	s_lshl_b32 s6, s11, 12
	v_bitop3_b32 v241, v18, s6, v17 bitop3:0xde
	v_readlane_b32 s6, v250, 7
	v_readlane_b32 s7, v250, 8
	s_lshl_b64 s[6:7], s[6:7], 2
	s_waitcnt lgkmcnt(0)
	s_add_u32 s4, s4, s6
	s_addc_u32 s5, s5, s7
	s_add_u32 s62, s70, 0x800000
	s_addc_u32 s63, s71, 0
	v_lshl_add_u64 v[2:3], v[2:3], 0, s[52:53]
	s_add_i32 m0, s34, 0x18000
	s_waitcnt vmcnt(18)
	s_barrier
	global_load_lds_dwordx4 v[2:3], off
	v_lshl_add_u64 v[2:3], v[4:5], 0, s[52:53]
	s_add_i32 m0, s34, 0x1a000
	s_add_i32 s90, s34, 0x8000
	global_load_lds_dwordx4 v[2:3], off
	v_lshl_add_u64 v[2:3], v[10:11], 0, s[52:53]
	s_mov_b32 m0, s90
	s_add_i32 s73, s34, 0xa000
	global_load_lds_dwordx4 v[2:3], off
	v_lshl_add_u64 v[2:3], v[12:13], 0, s[52:53]
	s_mov_b32 m0, s73
	v_writelane_b32 v250, s4, 27
	global_load_lds_dwordx4 v[2:3], off
	v_lshl_add_u64 v[2:3], v[6:7], 0, s[52:53]
	s_add_i32 m0, s34, 0x1c000
	v_writelane_b32 v250, s5, 28
	global_load_lds_dwordx4 v[2:3], off
	v_lshl_add_u64 v[2:3], v[8:9], 0, s[52:53]
	s_add_i32 m0, s34, 0x1e000
	s_cmpk_lt_u32 s2, 0x100
	global_load_lds_dwordx4 v[2:3], off
	s_cselect_b64 s[4:5], -1, 0
	s_lshl_b32 s6, s11, 14
	v_writelane_b32 v250, s11, 29
	s_or_b32 s6, s6, 0xfff80000
	v_writelane_b32 v250, s6, 30
	s_lshl_b32 s82, s15, 3
	v_readlane_b32 s6, v250, 21
	v_readlane_b32 s7, v250, 22
	v_readlane_b32 s61, v250, 20
	s_waitcnt vmcnt(6)
	v_add_f32_e32 v66, v66, v67
	v_add_f32_e32 v68, v68, v69
	v_add_f32_e32 v66, v66, v68
	v_add_f32_e32 v70, v70, v71
	v_add_f32_e32 v72, v72, v73
	v_add_f32_e32 v70, v70, v72
	v_add_f32_e32 v74, v74, v75
	v_add_f32_e32 v76, v76, v77
	v_add_f32_e32 v74, v74, v76
	v_add_f32_e32 v78, v78, v79
	v_add_f32_e32 v80, v80, v81
	v_add_f32_e32 v78, v78, v80
	v_add_f32_e32 v66, v66, v70
	v_add_f32_e32 v74, v74, v78
	v_add_f32_e32 v66, v66, v74
	v_fmamk_f32 v66, v66, 0x3a800000, v197
	v_rsq_f32_e32 v66, v66
	v_and_b32_e32 v65, 0xff, v195
	v_lshlrev_b32_e32 v65, 2, v65
	v_add_u32_e32 v65, 0x20800, v65
	ds_write_b32 v65, v66
	v_writelane_b32 v250, s95, 41
	v_and_b32_e32 v0, 1, v0
	v_cndmask_b32_e64 v2, 0, 1, s[6:7]
	s_lshr_b32 s6, s61, 6
	v_readfirstlane_b32 s36, v2
	v_cvt_f32_u32_e32 v2, s82
	v_writelane_b32 v250, s6, 31
	s_sub_i32 s6, 0, s82
	v_lshlrev_b32_e32 v20, 3, v19
	v_rcp_iflag_f32_e32 v2, v2
	v_lshlrev_b32_e32 v198, 16, v19
	v_lshl_or_b32 v242, s11, 5, v20
	s_mov_b32 s2, 0
	v_mul_f32_e32 v2, 0x4f7ffffe, v2
	v_cvt_u32_f32_e32 v2, v2
	v_cmp_eq_u32_e64 s[40:41], 0, v19
	v_or_b32_e32 v200, 0x4000, v198
	v_or_b32_e32 v202, 0x8000, v198
	v_readfirstlane_b32 s7, v2
	s_mul_i32 s6, s6, s7
	s_mul_hi_u32 s6, s7, s6
	s_add_i32 s6, s7, s6
	v_writelane_b32 v250, s6, 32
	v_lshlrev_b32_e32 v2, 1, v14
	v_lshl_add_u32 v206, v0, 6, v2
	v_and_b32_e32 v0, 1, v15
	v_lshlrev_b32_e32 v2, 1, v16
	v_readlane_b32 s6, v250, 12
	v_or_b32_e32 v204, 0xc000, v198
	s_mov_b32 s17, s31
	v_lshl_add_u32 v208, v0, 6, v2
	v_readlane_b32 s83, v250, 13
	s_mov_b32 s20, s6
	s_mov_b32 s11, s61
	s_mov_b64 s[12:13], s[8:9]
	s_mov_b64 s[6:7], s[96:97]
	s_waitcnt lgkmcnt(0)
	s_barrier
	s_branch .LBB0_259

; __device__ __forceinline__ void gemm_phase(LAS unsigned char* lds, const Sched& S, const Epi& E) {
;     ...
;         const bool has_next = S.next(ui + 1, nxt);
;         const char* nA = has_next ? nxt.a : cA; const char* nB = has_next ? nxt.b : cB;
;         const int nlda = has_next ? nxt.lda : lda, nldb = has_next ? nxt.ldb : ldb;
;         const size_t hA = (size_t)HALF * lda * 2;
;         const int nt = cur.nt;
;         const int nt_main = has_next ? nt : nt - 2;
;     ...
; #pragma unroll
;         for (int a = 0; a < 2; ++a)
; #pragma unroll
;             for (int b = 0; b < 2; ++b)
; #pragma unroll
;                 for (int m = 0; m < 4; ++m)
; #pragma unroll
;                     for (int n = 0; n < 2; ++n) acc[a][b][m][n] = (f32x4){0.f, 0.f, 0.f, 0.f};
.LBB0_261:
	s_mov_b32 s21, s31
	s_lshl_b64 s[66:67], s[20:21], 8
	s_add_i32 s21, s60, -2
	s_and_b64 s[26:27], s[42:43], exec
	s_cselect_b32 s68, s60, s21
	s_cmp_lt_i32 s68, 1
	s_cbranch_scc1 .LBB0_274
	s_add_u32 vcc_lo, s96, 0x80
	s_addc_u32 vcc_hi, s97, 0
	s_add_u32 s2, s8, 0x100
	s_addc_u32 s72, s9, 0
	v_mad_u64_u32 v[2:3], s[8:9], s20, v235, v[206:207]
	v_mov_b32_e32 v3, v1
	s_waitcnt lgkmcnt(0)
	v_lshl_add_u64 v[130:131], s[66:67], 0, v[2:3]
	v_mad_u64_u32 v[2:3], s[8:9], s20, v236, v[208:209]
	v_mov_b32_e32 v3, v1
	v_lshl_add_u64 v[132:133], s[66:67], 0, v[2:3]
	s_mov_b32 s3, s92
	s_mov_b32 s8, 0
	v_mov_b64_e32 v[2:3], 0
	v_mov_b64_e32 v[4:5], 0
	v_mov_b64_e32 v[6:7], 0
	v_mov_b64_e32 v[8:9], 0
	v_mov_b64_e32 v[10:11], 0
	v_mov_b64_e32 v[12:13], 0
	v_mov_b64_e32 v[14:15], 0
	v_mov_b64_e32 v[16:17], 0
	v_mov_b64_e32 v[18:19], 0
	v_mov_b64_e32 v[20:21], 0
	v_mov_b64_e32 v[22:23], 0
	v_mov_b64_e32 v[24:25], 0
	v_mov_b64_e32 v[26:27], 0
	v_mov_b64_e32 v[28:29], 0
	v_mov_b64_e32 v[30:31], 0
	v_mov_b64_e32 v[32:33], 0
	v_mov_b64_e32 v[34:35], 0
	v_mov_b64_e32 v[36:37], 0
	v_mov_b64_e32 v[38:39], 0
	v_mov_b64_e32 v[40:41], 0
	v_mov_b64_e32 v[42:43], 0
	v_mov_b64_e32 v[44:45], 0
	v_mov_b64_e32 v[46:47], 0
	v_mov_b64_e32 v[48:49], 0
	v_mov_b64_e32 v[50:51], 0
	v_mov_b64_e32 v[52:53], 0
	v_mov_b64_e32 v[54:55], 0
	v_mov_b64_e32 v[56:57], 0
	v_mov_b64_e32 v[58:59], 0
	v_mov_b64_e32 v[60:61], 0
	v_mov_b64_e32 v[62:63], 0
	v_mov_b64_e32 v[64:65], 0
	v_mov_b64_e32 v[66:67], 0
	v_mov_b64_e32 v[68:69], 0
	v_mov_b64_e32 v[70:71], 0
	v_mov_b64_e32 v[72:73], 0
	v_mov_b64_e32 v[74:75], 0
	v_mov_b64_e32 v[76:77], 0
	v_mov_b64_e32 v[78:79], 0
	v_mov_b64_e32 v[80:81], 0
	v_mov_b64_e32 v[82:83], 0
	v_mov_b64_e32 v[84:85], 0
	v_mov_b64_e32 v[86:87], 0
	v_mov_b64_e32 v[88:89], 0
	v_mov_b64_e32 v[90:91], 0
	v_mov_b64_e32 v[92:93], 0
	v_mov_b64_e32 v[94:95], 0
	v_mov_b64_e32 v[96:97], 0
	v_mov_b64_e32 v[98:99], 0
	v_mov_b64_e32 v[100:101], 0
	v_mov_b64_e32 v[102:103], 0
	v_mov_b64_e32 v[104:105], 0
	v_mov_b64_e32 v[106:107], 0
	v_mov_b64_e32 v[108:109], 0
	v_mov_b64_e32 v[110:111], 0
	v_mov_b64_e32 v[112:113], 0
	v_mov_b64_e32 v[114:115], 0
	v_mov_b64_e32 v[116:117], 0
	v_mov_b64_e32 v[118:119], 0
	v_mov_b64_e32 v[120:121], 0
	v_mov_b64_e32 v[122:123], 0
	v_mov_b64_e32 v[124:125], 0
	v_mov_b64_e32 v[126:127], 0
	v_mov_b64_e32 v[128:129], 0

; __device__ __forceinline__ unsigned xb_add(unsigned* p, unsigned v) { return __hip_atomic_fetch_add(p, v, __ATOMIC_RELAXED, __HIP_MEMORY_SCOPE_AGENT); }
; __device__ __forceinline__ void xcd_barrier(const XcdBarrier& b) {
;     asm volatile("s_waitcnt vmcnt(0)" ::: "memory");
;     __syncthreads();
;     if (threadIdx.x == 0) {
;         unsigned* bar = b.bar;
;         __builtin_amdgcn_s_waitcnt(0);
;         unsigned nloc = b.st[0], nx = b.st[1];
;         if (nloc == 0u) { xcd_barrier_complete(bar, b.x, nloc, nx); b.st[0] = nloc; b.st[1] = nx; }
;         const unsigned old = xb_add(&bar[XB_XSUB(b.x)], 1u);
;         const unsigned gen = old / nloc;
.Lmy_fullbar:
	s_waitcnt vmcnt(0)
	s_waitcnt vmcnt(0)
	s_barrier
	s_and_saveexec_b64 s[0:1], s[28:29]
	s_cbranch_execz .LBB0_446
	v_readlane_b32 s2, v251, 31
	s_waitcnt vmcnt(0) expcnt(0) lgkmcnt(0)
	s_nop 0
	v_mov_b32_e32 v0, s2
	ds_read_b32 v3, v0
	v_readlane_b32 s2, v251, 32
	s_waitcnt lgkmcnt(0)
	v_cmp_ne_u32_e32 vcc, 0, v3
	v_mov_b32_e32 v0, s2
	ds_read_b32 v0, v0
	s_cbranch_vccnz .LBB0_410
	s_mov_b32 s2, 1
	s_branch .LBB0_398
